# streaming stores of the hidden buffer (UP) and the conv-branch projections (PROJ) issued with system scope (sc0 sc1 nt instead of nt sc1)
# baseline (speedup 1.0000x reference)
.LBB0_152:
	v_mul_lo_u32 v144, v153, s50
	v_lshl_add_u32 v153, s51, 8, v147
	v_add_lshl_u32 v144, v153, v144, 1
	v_cvt_pk_bf16_f32 v124, v124, v125
	v_cvt_pk_bf16_f32 v125, v126, v127
	v_cvt_pk_bf16_f32 v126, v120, v121
	v_cvt_pk_bf16_f32 v127, v122, v123
	buffer_store_dwordx4 v[124:127], v144, s[16:19], 0 offen sc0 sc1 nt
	v_cvt_pk_bf16_f32 v112, v112, v113
	v_cvt_pk_bf16_f32 v113, v114, v115
	v_cvt_pk_bf16_f32 v114, v104, v105
	v_or_b32_e32 v104, 0x100, v144
	v_cvt_pk_bf16_f32 v115, v106, v107
	buffer_store_dwordx4 v[112:115], v104, s[16:19], 0 offen sc0 sc1 nt
	v_cvt_pk_bf16_f32 v104, v116, v117
	v_cvt_pk_bf16_f32 v105, v118, v119
	v_cvt_pk_bf16_f32 v106, v108, v109
	v_cvt_pk_bf16_f32 v107, v110, v111
	s_nop 1
	v_add_u32_e32 v112, 0xc000, v144
	buffer_store_dwordx4 v[104:107], v112, s[16:19], 0 offen sc0 sc1 nt
	v_cvt_pk_bf16_f32 v96, v96, v97
	v_cvt_pk_bf16_f32 v97, v98, v99
	v_cvt_pk_bf16_f32 v98, v88, v89
	v_or_b32_e32 v88, 0x100, v112
	v_cvt_pk_bf16_f32 v99, v90, v91
	buffer_store_dwordx4 v[96:99], v88, s[16:19], 0 offen sc0 sc1 nt
	v_cvt_pk_bf16_f32 v88, v100, v101
	v_cvt_pk_bf16_f32 v89, v102, v103
	v_cvt_pk_bf16_f32 v90, v92, v93
	v_cvt_pk_bf16_f32 v91, v94, v95
	s_nop 1
	v_add_u32_e32 v96, 0x18000, v144
	buffer_store_dwordx4 v[88:91], v96, s[16:19], 0 offen sc0 sc1 nt
	v_cvt_pk_bf16_f32 v80, v80, v81
	v_cvt_pk_bf16_f32 v81, v82, v83
	v_cvt_pk_bf16_f32 v82, v72, v73
	v_or_b32_e32 v72, 0x100, v96
	v_cvt_pk_bf16_f32 v83, v74, v75
	buffer_store_dwordx4 v[80:83], v72, s[16:19], 0 offen sc0 sc1 nt
	v_cvt_pk_bf16_f32 v72, v84, v85
	v_cvt_pk_bf16_f32 v73, v86, v87
	v_cvt_pk_bf16_f32 v74, v76, v77
	v_cvt_pk_bf16_f32 v75, v78, v79
	s_nop 1
	v_add_u32_e32 v80, 0x24000, v144
	buffer_store_dwordx4 v[72:75], v80, s[16:19], 0 offen sc0 sc1 nt
	v_cvt_pk_bf16_f32 v68, v68, v69
	v_cvt_pk_bf16_f32 v69, v70, v71
	v_cvt_pk_bf16_f32 v70, v64, v65
	v_or_b32_e32 v64, 0x100, v80
	v_cvt_pk_bf16_f32 v71, v66, v67
	buffer_store_dwordx4 v[68:71], v64, s[16:19], 0 offen sc0 sc1 nt
	v_add_u32_e32 v64, 0x60000, v144
	v_cvt_pk_bf16_f32 v60, v60, v61
	v_cvt_pk_bf16_f32 v61, v62, v63
	v_cvt_pk_bf16_f32 v62, v56, v57
	v_cvt_pk_bf16_f32 v63, v58, v59
	buffer_store_dwordx4 v[60:63], v64, s[16:19], 0 offen sc0 sc1 nt
	v_cvt_pk_bf16_f32 v48, v48, v49
	v_cvt_pk_bf16_f32 v49, v50, v51
	v_cvt_pk_bf16_f32 v50, v40, v41
	v_or_b32_e32 v40, 0x100, v64
	v_cvt_pk_bf16_f32 v51, v42, v43
	buffer_store_dwordx4 v[48:51], v40, s[16:19], 0 offen sc0 sc1 nt
	v_cvt_pk_bf16_f32 v40, v52, v53
	v_cvt_pk_bf16_f32 v41, v54, v55
	v_cvt_pk_bf16_f32 v42, v44, v45
	v_cvt_pk_bf16_f32 v43, v46, v47
	s_nop 1
	v_add_u32_e32 v48, 0x6c000, v144
	buffer_store_dwordx4 v[40:43], v48, s[16:19], 0 offen sc0 sc1 nt
	v_cvt_pk_bf16_f32 v32, v32, v33
	v_cvt_pk_bf16_f32 v33, v34, v35
	v_cvt_pk_bf16_f32 v34, v24, v25
	v_or_b32_e32 v24, 0x100, v48
	v_cvt_pk_bf16_f32 v35, v26, v27
	buffer_store_dwordx4 v[32:35], v24, s[16:19], 0 offen sc0 sc1 nt
	v_cvt_pk_bf16_f32 v24, v36, v37
	v_cvt_pk_bf16_f32 v25, v38, v39
	v_cvt_pk_bf16_f32 v26, v28, v29
	v_cvt_pk_bf16_f32 v27, v30, v31
	s_nop 1
	v_add_u32_e32 v32, 0x78000, v144
	buffer_store_dwordx4 v[24:27], v32, s[16:19], 0 offen sc0 sc1 nt
	v_cvt_pk_bf16_f32 v16, v16, v17
	v_cvt_pk_bf16_f32 v17, v18, v19
	v_cvt_pk_bf16_f32 v18, v8, v9
	v_or_b32_e32 v8, 0x100, v32
	v_cvt_pk_bf16_f32 v19, v10, v11
	buffer_store_dwordx4 v[16:19], v8, s[16:19], 0 offen sc0 sc1 nt
	v_cvt_pk_bf16_f32 v8, v20, v21
	v_cvt_pk_bf16_f32 v9, v22, v23
	v_cvt_pk_bf16_f32 v10, v12, v13
	v_cvt_pk_bf16_f32 v11, v14, v15
	s_nop 1
	v_add_u32_e32 v16, 0x84000, v144
	buffer_store_dwordx4 v[8:11], v16, s[16:19], 0 offen sc0 sc1 nt
	v_cvt_pk_bf16_f32 v4, v4, v5
	v_cvt_pk_bf16_f32 v5, v6, v7
	v_cvt_pk_bf16_f32 v6, v0, v1
	v_or_b32_e32 v0, 0x100, v16
	v_cvt_pk_bf16_f32 v7, v2, v3
	buffer_store_dwordx4 v[4:7], v0, s[16:19], 0 offen sc0 sc1 nt
	s_andn2_b64 vcc, exec, s[0:1]
	s_mov_b64 s[0:1], -1
	s_cbranch_vccnz .LBB0_141

.Lup_rs_ok:
	s_lshl_b32 s3, s50, 10
	s_add_i32 s17, s17, s3
	s_or_b32 s3, s17, s47
	v_or_b32_e32 v150, s3, v155
	v_lshl_or_b32 v150, v150, 7, v153
	v_pk_mul_f32 v[124:125], v[124:125], v[238:239] op_sel:[0,0] op_sel_hi:[1,0]
	v_pk_mul_f32 v[126:127], v[126:127], v[238:239] op_sel:[0,0] op_sel_hi:[1,0]
	v_pk_mul_f32 v[120:121], v[120:121], v[238:239] op_sel:[0,0] op_sel_hi:[1,0]
	v_pk_mul_f32 v[122:123], v[122:123], v[238:239] op_sel:[0,0] op_sel_hi:[1,0]
	v_max_f32_e32 v162, 0, v124
	v_max_f32_e32 v163, 0, v125
	v_max_f32_e32 v164, 0, v126
	v_max_f32_e32 v165, 0, v127
	v_max_f32_e32 v166, 0, v120
	v_max_f32_e32 v167, 0, v121
	v_max_f32_e32 v168, 0, v122
	v_max_f32_e32 v169, 0, v123
	v_pk_mul_f32 v[162:163], v[162:163], v[162:163]
	v_pk_mul_f32 v[164:165], v[164:165], v[164:165]
	v_pk_mul_f32 v[166:167], v[166:167], v[166:167]
	v_pk_mul_f32 v[168:169], v[168:169], v[168:169]
	v_cvt_pk_bf16_f32 v124, v162, v163
	v_cvt_pk_bf16_f32 v125, v164, v165
	v_cvt_pk_bf16_f32 v126, v166, v167
	v_cvt_pk_bf16_f32 v127, v168, v169
	s_mov_b32 s17, 0x0
	buffer_store_dwordx4 v[124:127], v150, s[4:7], s17 offen sc0 sc1 nt
	v_pk_mul_f32 v[116:117], v[116:117], v[238:239] op_sel:[0,0] op_sel_hi:[1,0]
	v_pk_mul_f32 v[118:119], v[118:119], v[238:239] op_sel:[0,0] op_sel_hi:[1,0]
	v_pk_mul_f32 v[112:113], v[112:113], v[238:239] op_sel:[0,0] op_sel_hi:[1,0]
	v_pk_mul_f32 v[114:115], v[114:115], v[238:239] op_sel:[0,0] op_sel_hi:[1,0]
	v_max_f32_e32 v170, 0, v116
	v_max_f32_e32 v171, 0, v117
	v_max_f32_e32 v172, 0, v118
	v_max_f32_e32 v173, 0, v119
	v_max_f32_e32 v174, 0, v112
	v_max_f32_e32 v175, 0, v113
	v_max_f32_e32 v176, 0, v114
	v_max_f32_e32 v177, 0, v115
	v_pk_mul_f32 v[170:171], v[170:171], v[170:171]
	v_pk_mul_f32 v[172:173], v[172:173], v[172:173]
	v_pk_mul_f32 v[174:175], v[174:175], v[174:175]
	v_pk_mul_f32 v[176:177], v[176:177], v[176:177]
	v_cvt_pk_bf16_f32 v116, v170, v171
	v_cvt_pk_bf16_f32 v117, v172, v173
	v_cvt_pk_bf16_f32 v118, v174, v175
	v_cvt_pk_bf16_f32 v119, v176, v177
	s_mov_b32 s17, 0x10000
	buffer_store_dwordx4 v[116:119], v150, s[4:7], s17 offen sc0 sc1 nt
	v_pk_mul_f32 v[108:109], v[108:109], v[238:239] op_sel:[0,1] op_sel_hi:[1,1]
	v_pk_mul_f32 v[110:111], v[110:111], v[238:239] op_sel:[0,1] op_sel_hi:[1,1]
	v_pk_mul_f32 v[104:105], v[104:105], v[238:239] op_sel:[0,1] op_sel_hi:[1,1]
	v_pk_mul_f32 v[106:107], v[106:107], v[238:239] op_sel:[0,1] op_sel_hi:[1,1]
	v_max_f32_e32 v162, 0, v108
	v_max_f32_e32 v163, 0, v109
	v_max_f32_e32 v164, 0, v110
	v_max_f32_e32 v165, 0, v111
	v_max_f32_e32 v166, 0, v104
	v_max_f32_e32 v167, 0, v105
	v_max_f32_e32 v168, 0, v106
	v_max_f32_e32 v169, 0, v107
	v_pk_mul_f32 v[162:163], v[162:163], v[162:163]
	v_pk_mul_f32 v[164:165], v[164:165], v[164:165]
	v_pk_mul_f32 v[166:167], v[166:167], v[166:167]
	v_pk_mul_f32 v[168:169], v[168:169], v[168:169]
	v_cvt_pk_bf16_f32 v108, v162, v163
	v_cvt_pk_bf16_f32 v109, v164, v165
	v_cvt_pk_bf16_f32 v110, v166, v167
	v_cvt_pk_bf16_f32 v111, v168, v169
	s_mov_b32 s17, 0x0
	buffer_store_dwordx4 v[108:111], v150, s[4:7], s17 offen offset:2048 sc0 sc1 nt
	v_pk_mul_f32 v[100:101], v[100:101], v[238:239] op_sel:[0,1] op_sel_hi:[1,1]
	v_pk_mul_f32 v[102:103], v[102:103], v[238:239] op_sel:[0,1] op_sel_hi:[1,1]
	v_pk_mul_f32 v[96:97], v[96:97], v[238:239] op_sel:[0,1] op_sel_hi:[1,1]
	v_pk_mul_f32 v[98:99], v[98:99], v[238:239] op_sel:[0,1] op_sel_hi:[1,1]
	v_max_f32_e32 v170, 0, v100
	v_max_f32_e32 v171, 0, v101
	v_max_f32_e32 v172, 0, v102
	v_max_f32_e32 v173, 0, v103
	v_max_f32_e32 v174, 0, v96
	v_max_f32_e32 v175, 0, v97
	v_max_f32_e32 v176, 0, v98
	v_max_f32_e32 v177, 0, v99
	v_pk_mul_f32 v[170:171], v[170:171], v[170:171]
	v_pk_mul_f32 v[172:173], v[172:173], v[172:173]
	v_pk_mul_f32 v[174:175], v[174:175], v[174:175]
	v_pk_mul_f32 v[176:177], v[176:177], v[176:177]
	v_cvt_pk_bf16_f32 v100, v170, v171
	v_cvt_pk_bf16_f32 v101, v172, v173
	v_cvt_pk_bf16_f32 v102, v174, v175
	v_cvt_pk_bf16_f32 v103, v176, v177
	s_mov_b32 s17, 0x10000
	buffer_store_dwordx4 v[100:103], v150, s[4:7], s17 offen offset:2048 sc0 sc1 nt
	v_pk_mul_f32 v[92:93], v[92:93], v[240:241] op_sel:[0,0] op_sel_hi:[1,0]
	v_pk_mul_f32 v[94:95], v[94:95], v[240:241] op_sel:[0,0] op_sel_hi:[1,0]
	v_pk_mul_f32 v[88:89], v[88:89], v[240:241] op_sel:[0,0] op_sel_hi:[1,0]
	v_pk_mul_f32 v[90:91], v[90:91], v[240:241] op_sel:[0,0] op_sel_hi:[1,0]
	v_max_f32_e32 v162, 0, v92
	v_max_f32_e32 v163, 0, v93
	v_max_f32_e32 v164, 0, v94
	v_max_f32_e32 v165, 0, v95
	v_max_f32_e32 v166, 0, v88
	v_max_f32_e32 v167, 0, v89
	v_max_f32_e32 v168, 0, v90
	v_max_f32_e32 v169, 0, v91
	v_pk_mul_f32 v[162:163], v[162:163], v[162:163]
	v_pk_mul_f32 v[164:165], v[164:165], v[164:165]
	v_pk_mul_f32 v[166:167], v[166:167], v[166:167]
	v_pk_mul_f32 v[168:169], v[168:169], v[168:169]
	v_cvt_pk_bf16_f32 v92, v162, v163
	v_cvt_pk_bf16_f32 v93, v164, v165
	v_cvt_pk_bf16_f32 v94, v166, v167
	v_cvt_pk_bf16_f32 v95, v168, v169
	s_mov_b32 s17, 0x1000
	buffer_store_dwordx4 v[92:95], v150, s[4:7], s17 offen sc0 sc1 nt
	v_pk_mul_f32 v[84:85], v[84:85], v[240:241] op_sel:[0,0] op_sel_hi:[1,0]
	v_pk_mul_f32 v[86:87], v[86:87], v[240:241] op_sel:[0,0] op_sel_hi:[1,0]
	v_pk_mul_f32 v[80:81], v[80:81], v[240:241] op_sel:[0,0] op_sel_hi:[1,0]
	v_pk_mul_f32 v[82:83], v[82:83], v[240:241] op_sel:[0,0] op_sel_hi:[1,0]
	v_max_f32_e32 v170, 0, v84
	v_max_f32_e32 v171, 0, v85
	v_max_f32_e32 v172, 0, v86
	v_max_f32_e32 v173, 0, v87
	v_max_f32_e32 v174, 0, v80
	v_max_f32_e32 v175, 0, v81
	v_max_f32_e32 v176, 0, v82
	v_max_f32_e32 v177, 0, v83
	v_pk_mul_f32 v[170:171], v[170:171], v[170:171]
	v_pk_mul_f32 v[172:173], v[172:173], v[172:173]
	v_pk_mul_f32 v[174:175], v[174:175], v[174:175]
	v_pk_mul_f32 v[176:177], v[176:177], v[176:177]
	v_cvt_pk_bf16_f32 v84, v170, v171
	v_cvt_pk_bf16_f32 v85, v172, v173
	v_cvt_pk_bf16_f32 v86, v174, v175
	v_cvt_pk_bf16_f32 v87, v176, v177
	s_mov_b32 s17, 0x11000
	buffer_store_dwordx4 v[84:87], v150, s[4:7], s17 offen sc0 sc1 nt
	v_pk_mul_f32 v[76:77], v[76:77], v[240:241] op_sel:[0,1] op_sel_hi:[1,1]
	v_pk_mul_f32 v[78:79], v[78:79], v[240:241] op_sel:[0,1] op_sel_hi:[1,1]
	v_pk_mul_f32 v[72:73], v[72:73], v[240:241] op_sel:[0,1] op_sel_hi:[1,1]
	v_pk_mul_f32 v[74:75], v[74:75], v[240:241] op_sel:[0,1] op_sel_hi:[1,1]
	v_max_f32_e32 v162, 0, v76
	v_max_f32_e32 v163, 0, v77
	v_max_f32_e32 v164, 0, v78
	v_max_f32_e32 v165, 0, v79
	v_max_f32_e32 v166, 0, v72
	v_max_f32_e32 v167, 0, v73
	v_max_f32_e32 v168, 0, v74
	v_max_f32_e32 v169, 0, v75
	v_pk_mul_f32 v[162:163], v[162:163], v[162:163]
	v_pk_mul_f32 v[164:165], v[164:165], v[164:165]
	v_pk_mul_f32 v[166:167], v[166:167], v[166:167]
	v_pk_mul_f32 v[168:169], v[168:169], v[168:169]
	v_cvt_pk_bf16_f32 v76, v162, v163
	v_cvt_pk_bf16_f32 v77, v164, v165
	v_cvt_pk_bf16_f32 v78, v166, v167
	v_cvt_pk_bf16_f32 v79, v168, v169
	s_mov_b32 s17, 0x1000
	buffer_store_dwordx4 v[76:79], v150, s[4:7], s17 offen offset:2048 sc0 sc1 nt
	v_pk_mul_f32 v[68:69], v[68:69], v[240:241] op_sel:[0,1] op_sel_hi:[1,1]
	v_pk_mul_f32 v[70:71], v[70:71], v[240:241] op_sel:[0,1] op_sel_hi:[1,1]
	v_pk_mul_f32 v[64:65], v[64:65], v[240:241] op_sel:[0,1] op_sel_hi:[1,1]
	v_pk_mul_f32 v[66:67], v[66:67], v[240:241] op_sel:[0,1] op_sel_hi:[1,1]
	v_max_f32_e32 v170, 0, v68
	v_max_f32_e32 v171, 0, v69
	v_max_f32_e32 v172, 0, v70
	v_max_f32_e32 v173, 0, v71
	v_max_f32_e32 v174, 0, v64
	v_max_f32_e32 v175, 0, v65
	v_max_f32_e32 v176, 0, v66
	v_max_f32_e32 v177, 0, v67
	v_pk_mul_f32 v[170:171], v[170:171], v[170:171]
	v_pk_mul_f32 v[172:173], v[172:173], v[172:173]
	v_pk_mul_f32 v[174:175], v[174:175], v[174:175]
	v_pk_mul_f32 v[176:177], v[176:177], v[176:177]
	v_cvt_pk_bf16_f32 v68, v170, v171
	v_cvt_pk_bf16_f32 v69, v172, v173
	v_cvt_pk_bf16_f32 v70, v174, v175
	v_cvt_pk_bf16_f32 v71, v176, v177
	s_mov_b32 s17, 0x11000
	buffer_store_dwordx4 v[68:71], v150, s[4:7], s17 offen offset:2048 sc0 sc1 nt
	v_pk_mul_f32 v[60:61], v[60:61], v[242:243] op_sel:[0,0] op_sel_hi:[1,0]
	v_pk_mul_f32 v[62:63], v[62:63], v[242:243] op_sel:[0,0] op_sel_hi:[1,0]
	v_pk_mul_f32 v[56:57], v[56:57], v[242:243] op_sel:[0,0] op_sel_hi:[1,0]
	v_pk_mul_f32 v[58:59], v[58:59], v[242:243] op_sel:[0,0] op_sel_hi:[1,0]
	v_max_f32_e32 v162, 0, v60
	v_max_f32_e32 v163, 0, v61
	v_max_f32_e32 v164, 0, v62
	v_max_f32_e32 v165, 0, v63
	v_max_f32_e32 v166, 0, v56
	v_max_f32_e32 v167, 0, v57
	v_max_f32_e32 v168, 0, v58
	v_max_f32_e32 v169, 0, v59
	v_pk_mul_f32 v[162:163], v[162:163], v[162:163]
	v_pk_mul_f32 v[164:165], v[164:165], v[164:165]
	v_pk_mul_f32 v[166:167], v[166:167], v[166:167]
	v_pk_mul_f32 v[168:169], v[168:169], v[168:169]
	v_cvt_pk_bf16_f32 v60, v162, v163
	v_cvt_pk_bf16_f32 v61, v164, v165
	v_cvt_pk_bf16_f32 v62, v166, v167
	v_cvt_pk_bf16_f32 v63, v168, v169
	s_mov_b32 s17, 0x4000
	buffer_store_dwordx4 v[60:63], v150, s[4:7], s17 offen sc0 sc1 nt
	v_pk_mul_f32 v[52:53], v[52:53], v[242:243] op_sel:[0,0] op_sel_hi:[1,0]
	v_pk_mul_f32 v[54:55], v[54:55], v[242:243] op_sel:[0,0] op_sel_hi:[1,0]
	v_pk_mul_f32 v[48:49], v[48:49], v[242:243] op_sel:[0,0] op_sel_hi:[1,0]
	v_pk_mul_f32 v[50:51], v[50:51], v[242:243] op_sel:[0,0] op_sel_hi:[1,0]
	v_max_f32_e32 v170, 0, v52
	v_max_f32_e32 v171, 0, v53
	v_max_f32_e32 v172, 0, v54
	v_max_f32_e32 v173, 0, v55
	v_max_f32_e32 v174, 0, v48
	v_max_f32_e32 v175, 0, v49
	v_max_f32_e32 v176, 0, v50
	v_max_f32_e32 v177, 0, v51
	v_pk_mul_f32 v[170:171], v[170:171], v[170:171]
	v_pk_mul_f32 v[172:173], v[172:173], v[172:173]
	v_pk_mul_f32 v[174:175], v[174:175], v[174:175]
	v_pk_mul_f32 v[176:177], v[176:177], v[176:177]
	v_cvt_pk_bf16_f32 v52, v170, v171
	v_cvt_pk_bf16_f32 v53, v172, v173
	v_cvt_pk_bf16_f32 v54, v174, v175
	v_cvt_pk_bf16_f32 v55, v176, v177
	s_mov_b32 s17, 0x14000
	buffer_store_dwordx4 v[52:55], v150, s[4:7], s17 offen sc0 sc1 nt
	v_pk_mul_f32 v[44:45], v[44:45], v[242:243] op_sel:[0,1] op_sel_hi:[1,1]
	v_pk_mul_f32 v[46:47], v[46:47], v[242:243] op_sel:[0,1] op_sel_hi:[1,1]
	v_pk_mul_f32 v[40:41], v[40:41], v[242:243] op_sel:[0,1] op_sel_hi:[1,1]
	v_pk_mul_f32 v[42:43], v[42:43], v[242:243] op_sel:[0,1] op_sel_hi:[1,1]
	v_max_f32_e32 v162, 0, v44
	v_max_f32_e32 v163, 0, v45
	v_max_f32_e32 v164, 0, v46
	v_max_f32_e32 v165, 0, v47
	v_max_f32_e32 v166, 0, v40
	v_max_f32_e32 v167, 0, v41
	v_max_f32_e32 v168, 0, v42
	v_max_f32_e32 v169, 0, v43
	v_pk_mul_f32 v[162:163], v[162:163], v[162:163]
	v_pk_mul_f32 v[164:165], v[164:165], v[164:165]
	v_pk_mul_f32 v[166:167], v[166:167], v[166:167]
	v_pk_mul_f32 v[168:169], v[168:169], v[168:169]
	v_cvt_pk_bf16_f32 v44, v162, v163
	v_cvt_pk_bf16_f32 v45, v164, v165
	v_cvt_pk_bf16_f32 v46, v166, v167
	v_cvt_pk_bf16_f32 v47, v168, v169
	s_mov_b32 s17, 0x4000
	buffer_store_dwordx4 v[44:47], v150, s[4:7], s17 offen offset:2048 sc0 sc1 nt
	v_pk_mul_f32 v[36:37], v[36:37], v[242:243] op_sel:[0,1] op_sel_hi:[1,1]
	v_pk_mul_f32 v[38:39], v[38:39], v[242:243] op_sel:[0,1] op_sel_hi:[1,1]
	v_pk_mul_f32 v[32:33], v[32:33], v[242:243] op_sel:[0,1] op_sel_hi:[1,1]
	v_pk_mul_f32 v[34:35], v[34:35], v[242:243] op_sel:[0,1] op_sel_hi:[1,1]
	v_max_f32_e32 v170, 0, v36
	v_max_f32_e32 v171, 0, v37
	v_max_f32_e32 v172, 0, v38
	v_max_f32_e32 v173, 0, v39
	v_max_f32_e32 v174, 0, v32
	v_max_f32_e32 v175, 0, v33
	v_max_f32_e32 v176, 0, v34
	v_max_f32_e32 v177, 0, v35
	v_pk_mul_f32 v[170:171], v[170:171], v[170:171]
	v_pk_mul_f32 v[172:173], v[172:173], v[172:173]
	v_pk_mul_f32 v[174:175], v[174:175], v[174:175]
	v_pk_mul_f32 v[176:177], v[176:177], v[176:177]
	v_cvt_pk_bf16_f32 v36, v170, v171
	v_cvt_pk_bf16_f32 v37, v172, v173
	v_cvt_pk_bf16_f32 v38, v174, v175
	v_cvt_pk_bf16_f32 v39, v176, v177
	s_mov_b32 s17, 0x14000
	buffer_store_dwordx4 v[36:39], v150, s[4:7], s17 offen offset:2048 sc0 sc1 nt
	v_pk_mul_f32 v[28:29], v[28:29], v[244:245] op_sel:[0,0] op_sel_hi:[1,0]
	v_pk_mul_f32 v[30:31], v[30:31], v[244:245] op_sel:[0,0] op_sel_hi:[1,0]
	v_pk_mul_f32 v[24:25], v[24:25], v[244:245] op_sel:[0,0] op_sel_hi:[1,0]
	v_pk_mul_f32 v[26:27], v[26:27], v[244:245] op_sel:[0,0] op_sel_hi:[1,0]
	v_max_f32_e32 v162, 0, v28
	v_max_f32_e32 v163, 0, v29
	v_max_f32_e32 v164, 0, v30
	v_max_f32_e32 v165, 0, v31
	v_max_f32_e32 v166, 0, v24
	v_max_f32_e32 v167, 0, v25
	v_max_f32_e32 v168, 0, v26
	v_max_f32_e32 v169, 0, v27
	v_pk_mul_f32 v[162:163], v[162:163], v[162:163]
	v_pk_mul_f32 v[164:165], v[164:165], v[164:165]
	v_pk_mul_f32 v[166:167], v[166:167], v[166:167]
	v_pk_mul_f32 v[168:169], v[168:169], v[168:169]
	v_cvt_pk_bf16_f32 v28, v162, v163
	v_cvt_pk_bf16_f32 v29, v164, v165
	v_cvt_pk_bf16_f32 v30, v166, v167
	v_cvt_pk_bf16_f32 v31, v168, v169
	s_mov_b32 s17, 0x5000
	buffer_store_dwordx4 v[28:31], v150, s[4:7], s17 offen sc0 sc1 nt
	v_pk_mul_f32 v[20:21], v[20:21], v[244:245] op_sel:[0,0] op_sel_hi:[1,0]
	v_pk_mul_f32 v[22:23], v[22:23], v[244:245] op_sel:[0,0] op_sel_hi:[1,0]
	v_pk_mul_f32 v[16:17], v[16:17], v[244:245] op_sel:[0,0] op_sel_hi:[1,0]
	v_pk_mul_f32 v[18:19], v[18:19], v[244:245] op_sel:[0,0] op_sel_hi:[1,0]
	v_max_f32_e32 v170, 0, v20
	v_max_f32_e32 v171, 0, v21
	v_max_f32_e32 v172, 0, v22
	v_max_f32_e32 v173, 0, v23
	v_max_f32_e32 v174, 0, v16
	v_max_f32_e32 v175, 0, v17
	v_max_f32_e32 v176, 0, v18
	v_max_f32_e32 v177, 0, v19
	v_pk_mul_f32 v[170:171], v[170:171], v[170:171]
	v_pk_mul_f32 v[172:173], v[172:173], v[172:173]
	v_pk_mul_f32 v[174:175], v[174:175], v[174:175]
	v_pk_mul_f32 v[176:177], v[176:177], v[176:177]
	v_cvt_pk_bf16_f32 v20, v170, v171
	v_cvt_pk_bf16_f32 v21, v172, v173
	v_cvt_pk_bf16_f32 v22, v174, v175
	v_cvt_pk_bf16_f32 v23, v176, v177
	s_mov_b32 s17, 0x15000
	buffer_store_dwordx4 v[20:23], v150, s[4:7], s17 offen sc0 sc1 nt
	v_pk_mul_f32 v[12:13], v[12:13], v[244:245] op_sel:[0,1] op_sel_hi:[1,1]
	v_pk_mul_f32 v[14:15], v[14:15], v[244:245] op_sel:[0,1] op_sel_hi:[1,1]
	v_pk_mul_f32 v[8:9], v[8:9], v[244:245] op_sel:[0,1] op_sel_hi:[1,1]
	v_pk_mul_f32 v[10:11], v[10:11], v[244:245] op_sel:[0,1] op_sel_hi:[1,1]
	v_max_f32_e32 v162, 0, v12
	v_max_f32_e32 v163, 0, v13
	v_max_f32_e32 v164, 0, v14
	v_max_f32_e32 v165, 0, v15
	v_max_f32_e32 v166, 0, v8
	v_max_f32_e32 v167, 0, v9
	v_max_f32_e32 v168, 0, v10
	v_max_f32_e32 v169, 0, v11
	v_pk_mul_f32 v[162:163], v[162:163], v[162:163]
	v_pk_mul_f32 v[164:165], v[164:165], v[164:165]
	v_pk_mul_f32 v[166:167], v[166:167], v[166:167]
	v_pk_mul_f32 v[168:169], v[168:169], v[168:169]
	v_cvt_pk_bf16_f32 v12, v162, v163
	v_cvt_pk_bf16_f32 v13, v164, v165
	v_cvt_pk_bf16_f32 v14, v166, v167
	v_cvt_pk_bf16_f32 v15, v168, v169
	s_mov_b32 s17, 0x5000
	buffer_store_dwordx4 v[12:15], v150, s[4:7], s17 offen offset:2048 sc0 sc1 nt
	v_pk_mul_f32 v[4:5], v[4:5], v[244:245] op_sel:[0,1] op_sel_hi:[1,1]
	v_pk_mul_f32 v[6:7], v[6:7], v[244:245] op_sel:[0,1] op_sel_hi:[1,1]
	v_pk_mul_f32 v[0:1], v[0:1], v[244:245] op_sel:[0,1] op_sel_hi:[1,1]
	v_pk_mul_f32 v[2:3], v[2:3], v[244:245] op_sel:[0,1] op_sel_hi:[1,1]
	v_max_f32_e32 v170, 0, v4
	v_max_f32_e32 v171, 0, v5
	v_max_f32_e32 v172, 0, v6
	v_max_f32_e32 v173, 0, v7
	v_max_f32_e32 v174, 0, v0
	v_max_f32_e32 v175, 0, v1
	v_max_f32_e32 v176, 0, v2
	v_max_f32_e32 v177, 0, v3
	v_pk_mul_f32 v[170:171], v[170:171], v[170:171]
	v_pk_mul_f32 v[172:173], v[172:173], v[172:173]
	v_pk_mul_f32 v[174:175], v[174:175], v[174:175]
	v_pk_mul_f32 v[176:177], v[176:177], v[176:177]
	v_cvt_pk_bf16_f32 v4, v170, v171
	v_cvt_pk_bf16_f32 v5, v172, v173
	v_cvt_pk_bf16_f32 v6, v174, v175
	v_cvt_pk_bf16_f32 v7, v176, v177
	s_mov_b32 s17, 0x15000
	buffer_store_dwordx4 v[4:7], v150, s[4:7], s17 offen offset:2048 sc0 sc1 nt
	s_andn2_b64 vcc, exec, s[0:1]
	s_mov_b64 s[0:1], -1
	s_cbranch_vccnz .LBB0_682
	s_andn2_b64 vcc, exec, s[10:11]
	s_cbranch_vccnz .LBB0_681
	s_barrier
	s_branch .LBB0_681
